# readout bonus term: per-lane partial sums (r*r_k*kd over 4 columns) stored by the scan staging waves, readout loads two floats instead of r,k,a0,a1 (f32 math unchanged up to summation order)
# speedup vs baseline: 1.0073x; 1.0073x over previous
.LBB0_600:
	v_writelane_b32 v255, s88, 20
	s_nop 1
	v_writelane_b32 v255, s89, 21
	s_or_b64 exec, exec, s[6:7]
	s_waitcnt lgkmcnt(0)
	v_mov_b32_e32 v0, v254
	v_mov_b64_e32 v[2:3], s[58:59]
	s_barrier
	flat_load_dwordx2 v[4:5], v[2:3] offset:192 sc0 sc1
	flat_load_dwordx2 v[6:7], v[2:3] offset:200 sc0 sc1
	flat_load_dwordx2 v[188:189], v[2:3] offset:208 sc0 sc1
	s_waitcnt vmcnt(0)
	s_add_u32 s66, s26, 0x13800000
	s_addc_u32 s67, s27, 0
	s_add_u32 s68, s26, 0x15900000
	s_addc_u32 s69, s27, 0
	s_add_u32 s64, s26, 0x2800000
	s_addc_u32 s65, s27, 0
	s_add_u32 s4, s26, 0x2dc00000
	s_addc_u32 s5, s27, 0
	v_writelane_b32 v255, s4, 22
	v_readfirstlane_b32 s0, v0
	s_waitcnt lgkmcnt(0)
	v_readfirstlane_b32 s71, v5
	v_writelane_b32 v255, s5, 23
	s_add_u32 s4, s26, 0x2b000000
	s_addc_u32 s5, s27, 0
	v_writelane_b32 v255, s4, 24
	v_readfirstlane_b32 s70, v4
	v_readfirstlane_b32 s73, v7
	v_writelane_b32 v255, s5, 25
	s_add_u32 s4, s26, 0x12a00000
	s_addc_u32 s5, s27, 0
	s_add_u32 s54, s26, 0x11200000
	v_writelane_b32 v255, s4, 26
	s_addc_u32 s55, s27, 0
	s_add_u32 s58, s26, 0x5c00000
	v_writelane_b32 v255, s5, 27
	s_addc_u32 s59, s27, 0
	v_readlane_b32 s4, v255, 7
	s_add_u32 s62, s26, 0x3000000
	v_readlane_b32 s5, v255, 8
	s_addc_u32 s63, s27, 0
	s_and_b64 vcc, exec, s[4:5]
	v_readfirstlane_b32 s72, v6
	s_cbranch_vccz .LBB0_732
	v_readlane_b32 s4, v255, 10
	v_readlane_b32 s5, v255, 11
	s_nop 1
	v_mov_b64_e32 v[2:3], s[4:5]
	flat_load_dwordx2 v[4:5], v[2:3] offset:80 sc0 sc1
	flat_load_dwordx2 v[6:7], v[2:3] offset:72 sc0 sc1
	flat_load_dwordx2 v[8:9], v[2:3] offset:64 sc0 sc1
	flat_load_dwordx2 v[10:11], v[2:3] offset:336 sc0 sc1
	flat_load_dwordx2 v[12:13], v[2:3] offset:232 sc0 sc1
	flat_load_dwordx2 v[14:15], v[2:3] offset:120 sc0 sc1
	s_waitcnt vmcnt(0) lgkmcnt(0)
	v_readfirstlane_b32 s76, v4
	v_readfirstlane_b32 s77, v5
	v_readfirstlane_b32 s78, v6
	v_readfirstlane_b32 s79, v7
	v_readfirstlane_b32 s80, v8
	v_readfirstlane_b32 s81, v9
	v_readfirstlane_b32 s82, v10
	v_readfirstlane_b32 s83, v11
	v_readfirstlane_b32 s84, v12
	v_readfirstlane_b32 s85, v13
	v_readfirstlane_b32 s6, v14
	v_readfirstlane_b32 s7, v15
	s_ashr_i32 s0, s0, 6
	v_and_b32_e32 v2, 15, v0
	v_bfe_u32 v131, v0, 4, 4
	s_add_i32 s23, s0, -4
	s_mulk_i32 s0, 0x2100
	v_lshlrev_b32_e32 v6, 3, v0
	v_lshlrev_b32_e32 v4, 8, v131
	v_lshlrev_b32_e32 v5, 4, v2
	s_add_i32 s0, s0, 0
	v_bfe_u32 v148, v0, 3, 3
	v_and_b32_e32 v6, 56, v6
	v_writelane_b32 v255, s6, 28
	s_movk_i32 s1, 0xff
	v_or_b32_e32 v136, 16, v131
	v_add3_u32 v141, 0, v4, v5
	v_and_b32_e32 v4, 0xf0, v0
	s_add_i32 s0, s0, 0x14c00
	v_mul_u32_u24_e32 v10, 0x84, v6
	v_lshlrev_b32_e32 v11, 2, v148
	v_writelane_b32 v255, s7, 29
	v_cmp_lt_i32_e64 s[6:7], s1, v0
	s_movk_i32 s1, 0x100
	v_lshlrev_b32_e32 v142, 2, v4
	v_lshlrev_b32_e32 v4, 8, v136
	v_add3_u32 v149, s0, v10, v11
	v_mov_b32_e32 v10, 5
	v_ashrrev_i32_e32 v99, 4, v0
	v_cmp_gt_i32_e64 s[8:9], s1, v0
	v_add3_u32 v145, 0, v4, v5
	v_and_b32_e32 v7, 7, v0
	v_bfe_u32 v147, v0, 5, 1
	v_and_b32_e32 v4, 31, v0
	v_lshlrev_b32_sdwa v153, v10, v0 dst_sel:DWORD dst_unused:UNUSED_PAD src0_sel:DWORD src1_sel:BYTE_0
	v_or_b32_sdwa v0, v0, s1 dst_sel:DWORD dst_unused:UNUSED_PAD src0_sel:BYTE_0 src1_sel:DWORD
	s_movk_i32 s4, 0x20ff
	v_lshrrev_b32_e32 v154, 4, v0
	v_lshlrev_b32_e32 v155, 5, v0
	v_mov_b32_e32 v0, 0xa040
	v_bitop3_b32 v140, v131, s4, 16 bitop3:0x36
	v_lshlrev_b32_e32 v3, 6, v131
	s_movk_i32 s4, 0xff40
	v_lshl_add_u32 v8, v4, 2, s0
	v_mul_u32_u24_e32 v9, 0x84, v147
	v_lshl_add_u32 v160, v99, 2, v0
	v_lshlrev_b32_e32 v0, 2, v7
	v_lshlrev_b32_e32 v98, 2, v2
	v_or_b32_e32 v137, 0x2000, v131
	v_xor_b32_e32 v138, 0x20ff, v131
	v_cmp_gt_u32_e64 s[10:11], 4, v2
	v_mov_b32_e32 v1, 0
	v_or_b32_e32 v139, 0x2010, v131
	s_mov_b32 s87, 0
	v_add3_u32 v143, 0, v142, v5
	v_lshlrev_b32_e32 v144, 6, v136
	v_mad_i32_i24 v146, v136, s4, v145
	v_or_b32_e32 v150, 8, v148
	v_or_b32_e32 v151, 16, v148
	v_or_b32_e32 v152, 24, v148
	v_or_b32_e32 v156, 0x1fe0, v131
	v_xor_b32_e32 v157, 31, v131
	v_or_b32_e32 v158, 0x1fe0, v154
	v_xor_b32_e32 v159, 31, v154
	v_or_b32_e32 v161, 0x100, v5
	v_lshl_or_b32 v162, v99, 5, v0
	s_mov_b32 s74, 0xf800000
	v_mov_b32_e32 v163, 0x260
	v_lshlrev_b32_e32 v100, 1, v2
	s_mov_b32 s75, 0xa800
	s_movk_i32 s40, 0x7fff
	s_mov_b32 s41, 0xac00
	s_movk_i32 s20, 0x15ff
	s_movk_i32 s21, 0x2bff
	s_movk_i32 s46, 0x41ff
	s_movk_i32 s47, 0x59ff
	s_movk_i32 s24, 0x61ff
	s_movk_i32 s44, 0x77ff
	s_mov_b32 s45, 0x8dff
	v_add_u32_e32 v164, v8, v9
	v_lshlrev_b32_e32 v102, 1, v6
	v_lshlrev_b32_e32 v104, 2, v4
	v_lshlrev_b32_e32 v165, 2, v3
	s_add_i32 s25, 0, 0x19000
	v_mov_b32_e32 v166, 7
	v_mov_b32_e32 v167, 0xa800
	s_mov_b32 s33, s2
	s_branch .LBB0_603

.LBB0_603:
	s_lshl_b32 s0, s33, 4
	s_and_b32 s28, s0, 0x7c0
	s_waitcnt vmcnt(0)
	v_or_b32_e32 v2, s28, v98
	v_lshlrev_b32_e32 v0, 2, v2
	v_lshl_add_u64 v[4:5], s[70:71], 0, v[0:1]
	flat_load_dwordx4 v[42:45], v[4:5]
	v_lshl_add_u64 v[4:5], s[72:73], 0, v[0:1]
	flat_load_dwordx4 v[46:49], v[4:5]
	s_ashr_i32 s14, s33, 7
	s_cmpk_lt_u32 s33, 0x80
	s_cselect_b64 s[12:13], -1, 0
	s_cmpk_gt_u32 s33, 0x7f
	s_cselect_b64 s[88:89], -1, 0
	v_lshl_add_u64 v[4:5], v[188:189], 0, v[0:1]
	flat_load_dwordx4 v[190:193], v[4:5]
	v_mov_b32_e32 v198, 0x9200000
	v_mov_b32_e32 v199, 0xd200000
	v_cndmask_b32_e64 v198, v198, v199, s[88:89]
	v_add_u32_e32 v198, v198, v2
	v_mov_b32_e32 v199, 0
	v_lshl_add_u64 v[198:199], s[26:27], 0, v[198:199]
	s_and_saveexec_b64 s[4:5], s[8:9]
	s_xor_b64 s[4:5], exec, s[4:5]
	s_lshl_b32 s0, s14, 11
	s_ashr_i32 s1, s0, 31
	s_or_saveexec_b64 s[16:17], s[4:5]
	s_and_b32 s4, s33, 3
	v_mov_b64_e32 v[4:5], s[0:1]
	v_lshlrev_b32_e32 v2, 1, v2
	s_xor_b64 exec, exec, s[16:17]
	s_cbranch_execz .LBB0_615
	v_cndmask_b32_e64 v4, v138, v137, s[12:13]
	v_lshlrev_b32_e32 v6, 13, v4
	v_mov_b32_e32 v7, v1
	v_lshlrev_b32_e32 v12, 14, v4
	v_mov_b32_e32 v13, v1
	s_lshl_b32 s18, s14, 11
	v_lshl_add_u64 v[8:9], s[48:49], 0, v[6:7]
	v_lshl_add_u64 v[12:13], s[60:61], 0, v[12:13]
	s_ashr_i32 s19, s18, 31
	v_lshl_add_u64 v[6:7], s[52:53], 0, v[6:7]
	v_lshl_add_u64 v[8:9], v[8:9], 0, v[0:1]
	v_lshlrev_b32_e32 v10, 12, v4
	v_mov_b32_e32 v11, v1
	v_lshl_add_u64 v[12:13], s[18:19], 2, v[12:13]
	v_lshl_add_u64 v[6:7], s[18:19], 1, v[6:7]
	v_mov_b32_e32 v3, v1
	v_lshl_add_u64 v[12:13], v[12:13], 0, v[0:1]
	global_load_dwordx4 v[34:37], v[8:9], off
	global_load_dwordx4 v[38:41], v[12:13], off
	v_lshl_add_u64 v[6:7], v[6:7], 0, v[2:3]
	v_lshl_add_u64 v[8:9], s[66:67], 0, v[10:11]
	v_lshl_add_u64 v[8:9], v[8:9], 0, v[2:3]
	global_load_dwordx2 v[110:111], v[6:7], off
	global_load_dwordx2 v[112:113], v[8:9], off
	s_and_saveexec_b64 s[0:1], s[10:11]
	s_cbranch_execz .LBB0_608
	v_lshlrev_b32_e32 v4, 11, v4
	v_lshlrev_b32_e32 v4, 1, v4
	v_mov_b32_e32 v5, v1
	v_lshl_add_u64 v[4:5], s[68:69], 0, v[4:5]
	s_lshl_b32 s86, s28, 1
	v_lshl_add_u64 v[4:5], v[4:5], 0, s[86:87]
	s_lshl_b32 s86, s4, 5
	v_lshl_add_u64 v[4:5], v[4:5], 0, s[86:87]
	v_lshlrev_b32_e32 v6, 1, v98
	v_mov_b32_e32 v7, v1
	v_lshl_add_u64 v[4:5], v[4:5], 0, v[6:7]
	global_load_dwordx2 v[106:107], v[4:5], off

.LBB0_728:
	s_or_b64 exec, exec, s[0:1]
	v_cmp_lt_u32_e32 vcc, 7, v64
	s_and_saveexec_b64 s[0:1], vcc
	s_cbranch_execz .Lscan_bonus_a
	v_pk_mul_f32 v[194:195], v[74:75], v[190:191]
	v_pk_mul_f32 v[196:197], v[76:77], v[192:193]
	v_pk_mul_f32 v[194:195], v[194:195], v[66:67]
	v_lshl_add_u32 v200, v64, 5, v131
	v_pk_fma_f32 v[194:195], v[196:197], v[68:69], v[194:195]
	v_sub_u32_e32 v201, 0x20ff, v200
	v_add_u32_e32 v200, 0xffffff00, v200
	v_cndmask_b32_e64 v200, v200, v201, s[88:89]
	v_add_f32_e32 v194, v194, v195
	v_lshlrev_b32_e32 v200, 11, v200
	v_mov_b32_e32 v201, 0
	v_lshl_add_u64 v[200:201], v[198:199], 0, v[200:201]
	global_store_dword v[200:201], v194, off

.Lscan_stage_tail:
	s_or_b64 exec, exec, s[0:1]
	v_cmp_lt_u32_e32 vcc, 7, v64
	s_and_saveexec_b64 s[0:1], vcc
	s_cbranch_execz .Lscan_bonus_b
	v_pk_mul_f32 v[194:195], v[74:75], v[190:191]
	v_pk_mul_f32 v[196:197], v[76:77], v[192:193]
	v_pk_mul_f32 v[194:195], v[194:195], v[66:67]
	v_lshl_add_u32 v200, v64, 5, v136
	v_pk_fma_f32 v[194:195], v[196:197], v[68:69], v[194:195]
	v_sub_u32_e32 v201, 0x20ff, v200
	v_add_u32_e32 v200, 0xffffff00, v200
	v_cndmask_b32_e64 v200, v200, v201, s[88:89]
	v_add_f32_e32 v194, v194, v195
	v_lshlrev_b32_e32 v200, 11, v200
	v_mov_b32_e32 v201, 0
	v_lshl_add_u64 v[200:201], v[198:199], 0, v[200:201]
	global_store_dword v[200:201], v194, off

.LBB0_784:
	s_or_b64 exec, exec, s[6:7]
	v_readlane_b32 s0, v255, 10
	v_readlane_b32 s1, v255, 11
	s_waitcnt lgkmcnt(0)
	v_mov_b32_e32 v0, v254
	s_waitcnt vmcnt(0)
	v_mov_b64_e32 v[2:3], s[0:1]
	s_barrier
	flat_load_dwordx2 v[4:5], v[2:3] offset:200 sc0 sc1
	flat_load_dwordx2 v[6:7], v[2:3] offset:208 sc0 sc1
	flat_load_dwordx2 v[8:9], v[2:3] offset:216 sc0 sc1
	flat_load_dwordx2 v[2:3], v[2:3] offset:224 sc0 sc1
	s_waitcnt vmcnt(0)
	s_add_u32 s8, s26, 0xf200000
	v_readfirstlane_b32 s0, v0
	s_addc_u32 s9, s27, 0
	s_ashr_i32 s0, s0, 6
	v_readlane_b32 s1, v255, 6
	s_add_i32 s20, s0, s1
	s_cmp_lt_i32 s20, 0x10000
	s_waitcnt lgkmcnt(0)
	v_readfirstlane_b32 s11, v5
	v_readfirstlane_b32 s10, v4
	v_readfirstlane_b32 s13, v7
	v_readfirstlane_b32 s12, v6
	v_readfirstlane_b32 s15, v9
	v_readfirstlane_b32 s14, v8
	v_readfirstlane_b32 s17, v3
	v_readfirstlane_b32 s16, v2
	s_cbranch_scc0 .LBB0_787
	s_add_u32 s18, s26, 0xb200000
	s_addc_u32 s19, s27, 0
	v_lshlrev_b32_e32 v0, 2, v0
	s_lshl_b32 s1, s2, 11
	s_lshl_b32 s0, s0, 8
	v_and_b32_e32 v2, 0xfc, v0
	s_add_i32 s21, s1, s0
	s_lshl_b32 s23, s30, 11
	v_mov_b32_e32 v3, 0x3a27c5ac
	s_mov_b32 s24, 0xf800000
	v_mov_b32_e32 v4, 0x260
	v_mov_b32_e32 v1, 0
	s_movk_i32 s25, 0x1000
	s_and_b32 s0, s21, 0x700
	v_or_b32_e32 v124, s0, v2
	v_lshlrev_b32_e32 v120, 2, v124
	global_load_dwordx4 v[60:63], v120, s[14:15]
	global_load_dwordx4 v[64:67], v120, s[16:17]
	s_min_i32 s0, s20, 0xffff
	s_ashr_i32 s0, s0, 3
	s_lshl_b32 s1, s0, 11
	v_add_u32_e32 v121, s1, v124
	v_lshlrev_b32_e32 v98, 1, v121
	v_add_u32_e32 v121, 0x2000000, v121
	global_load_dwordx2 v[80:81], v98, s[38:39]
	global_load_dwordx2 v[82:83], v98, s[18:19]
	global_load_dwordx2 v[86:87], v98, s[68:69]
	global_load_dwordx2 v[88:89], v98, s[56:57]
	global_load_dword v94, v121, s[38:39]
	global_load_dword v95, v121, s[18:19]
	s_add_i32 s20, s20, s22
	s_min_i32 s0, s20, 0xffff
	s_ashr_i32 s0, s0, 3
	s_lshl_b32 s1, s0, 11
	v_add_u32_e32 v121, s1, v124
	v_lshlrev_b32_e32 v118, 1, v121
	v_add_u32_e32 v121, 0x2000000, v121
	global_load_dwordx2 v[100:101], v118, s[38:39]
	global_load_dwordx2 v[102:103], v118, s[18:19]
	global_load_dwordx2 v[106:107], v118, s[68:69]
	global_load_dwordx2 v[108:109], v118, s[56:57]
	global_load_dword v114, v121, s[38:39]
	global_load_dword v115, v121, s[18:19]
	s_add_i32 s20, s20, s22
	s_movk_i32 s4, 16
.Lp6_loop:
	s_waitcnt vmcnt(6)
	v_mov_b64_e32 v[28:29], v[80:81]
	v_mov_b64_e32 v[30:31], v[82:83]
	v_mov_b64_e32 v[34:35], v[86:87]
	v_mov_b64_e32 v[36:37], v[88:89]
	v_mov_b64_e32 v[42:43], v[94:95]
	v_mov_b32_e32 v26, v98
	v_mov_b64_e32 v[6:7], v[60:61]
	v_mov_b64_e32 v[8:9], v[62:63]
	v_mov_b64_e32 v[10:11], v[64:65]
	v_mov_b64_e32 v[12:13], v[66:67]
	s_min_i32 s0, s20, 0xffff
	s_ashr_i32 s0, s0, 3
	s_lshl_b32 s1, s0, 11
	v_add_u32_e32 v121, s1, v124
	v_lshlrev_b32_e32 v98, 1, v121
	v_add_u32_e32 v121, 0x2000000, v121
	global_load_dwordx2 v[80:81], v98, s[38:39]
	global_load_dwordx2 v[82:83], v98, s[18:19]
	global_load_dwordx2 v[86:87], v98, s[68:69]
	global_load_dwordx2 v[88:89], v98, s[56:57]
	global_load_dword v94, v121, s[38:39]
	global_load_dword v95, v121, s[18:19]
	s_add_i32 s20, s20, s22
	v_lshlrev_b32_e32 v44, 16, v28
	v_and_b32_e32 v45, 0xffff0000, v28
	v_lshlrev_b32_e32 v28, 16, v29
	v_and_b32_e32 v29, 0xffff0000, v29
	v_lshlrev_b32_e32 v46, 16, v30
	v_and_b32_e32 v47, 0xffff0000, v30
	v_lshlrev_b32_e32 v30, 16, v31
	v_and_b32_e32 v31, 0xffff0000, v31
	v_pk_add_f32 v[28:29], v[28:29], v[30:31]
	v_pk_add_f32 v[30:31], v[44:45], v[46:47]
	v_add_f32_e32 v0, v30, v31
	v_add_f32_e32 v0, v28, v0
	v_add_f32_e32 v0, v29, v0
	s_nop 1
	v_add_f32_dpp v0, v0, v0 quad_perm:[1,0,3,2] row_mask:0xf bank_mask:0xf bound_ctrl:1
	s_nop 0
	v_add_f32_dpp v0, v0, v0 quad_perm:[2,3,0,1] row_mask:0xf bank_mask:0xf bound_ctrl:1
	s_nop 1
	v_add_f32_dpp v0, v0, v0 row_half_mirror row_mask:0xf bank_mask:0xf bound_ctrl:1
	s_nop 1
	v_add_f32_dpp v0, v0, v0 row_ror:8 row_mask:0xf bank_mask:0xf bound_ctrl:1
	v_fmamk_f32 v31, v0, 0xbc800000, v31
	v_fmac_f32_e32 v30, 0xbc800000, v0
	v_fmamk_f32 v29, v0, 0xbc800000, v29
	v_fmac_f32_e32 v28, 0xbc800000, v0
	v_pk_mul_f32 v[18:19], v[30:31], v[30:31]
	v_pk_mul_f32 v[14:15], v[28:29], v[28:29]
	v_add_f32_e32 v5, v18, v19
	v_add_f32_e32 v5, v14, v5
	v_add_f32_e32 v5, v15, v5
	v_add_f32_e32 v0, v42, v43
	v_lshlrev_b32_e32 v50, 16, v34
	v_add_f32_dpp v5, v5, v5 quad_perm:[1,0,3,2] row_mask:0xf bank_mask:0xf bound_ctrl:1
	v_add_f32_dpp v0, v0, v0 quad_perm:[1,0,3,2] row_mask:0xf bank_mask:0xf bound_ctrl:1
	v_and_b32_e32 v51, 0xffff0000, v34
	v_add_f32_dpp v5, v5, v5 quad_perm:[2,3,0,1] row_mask:0xf bank_mask:0xf bound_ctrl:1
	v_add_f32_dpp v0, v0, v0 quad_perm:[2,3,0,1] row_mask:0xf bank_mask:0xf bound_ctrl:1
	v_lshlrev_b32_e32 v34, 16, v35
	v_add_f32_dpp v5, v5, v5 row_half_mirror row_mask:0xf bank_mask:0xf bound_ctrl:1
	v_add_f32_dpp v0, v0, v0 row_half_mirror row_mask:0xf bank_mask:0xf bound_ctrl:1
	v_and_b32_e32 v35, 0xffff0000, v35
	v_add_f32_dpp v5, v5, v5 row_ror:8 row_mask:0xf bank_mask:0xf bound_ctrl:1
	v_fmamk_f32 v5, v5, 0x3c800000, v3
	v_mul_f32_e32 v14, 0x4f800000, v5
	v_cmp_gt_f32_e32 vcc, s24, v5
	v_add_f32_dpp v0, v0, v0 row_ror:8 row_mask:0xf bank_mask:0xf bound_ctrl:1
	v_lshlrev_b32_e32 v52, 16, v36
	v_cndmask_b32_e32 v5, v5, v14, vcc
	v_sqrt_f32_e32 v14, v5
	v_and_b32_e32 v53, 0xffff0000, v36
	v_lshlrev_b32_e32 v36, 16, v37
	v_and_b32_e32 v37, 0xffff0000, v37
	v_add_u32_e32 v15, -1, v14
	v_add_u32_e32 v16, 1, v14
	v_fma_f32 v17, -v15, v14, v5
	v_fma_f32 v18, -v16, v14, v5
	v_cmp_ge_f32_e64 s[6:7], 0, v17
	s_nop 1
	v_cndmask_b32_e64 v14, v14, v15, s[6:7]
	v_cmp_lt_f32_e64 s[6:7], 0, v18
	s_nop 1
	v_cndmask_b32_e64 v14, v14, v16, s[6:7]
	v_mul_f32_e32 v15, 0x37800000, v14
	v_cndmask_b32_e32 v14, v14, v15, vcc
	v_cmp_class_f32_e32 vcc, v5, v4
	s_nop 1
	v_cndmask_b32_e32 v5, v14, v5, vcc
	v_div_scale_f32 v14, s[0:1], v5, v5, 1.0
	v_rcp_f32_e32 v16, v14
	v_div_scale_f32 v15, vcc, 1.0, v5, 1.0
	v_fma_f32 v17, -v14, v16, 1.0
	v_fmac_f32_e32 v16, v17, v16
	v_mul_f32_e32 v17, v15, v16
	v_fma_f32 v18, -v14, v17, v15
	v_fmac_f32_e32 v17, v18, v16
	v_fma_f32 v14, -v14, v17, v15
	v_div_fmas_f32 v14, v14, v16, v17
	v_div_fixup_f32 v14, v14, v5, 1.0
	v_pk_mul_f32 v[16:17], v[30:31], v[14:15] op_sel_hi:[1,0]
	v_pk_mul_f32 v[14:15], v[28:29], v[14:15] op_sel_hi:[1,0]
	v_pk_fma_f32 v[6:7], v[6:7], v[16:17], v[10:11]
	v_pk_fma_f32 v[8:9], v[8:9], v[14:15], v[12:13]
	v_pk_fma_f32 v[6:7], v[0:1], v[50:51], v[6:7] op_sel_hi:[0,1,1]
	v_pk_fma_f32 v[8:9], v[0:1], v[34:35], v[8:9] op_sel_hi:[0,1,1]
	v_pk_mul_f32 v[6:7], v[6:7], v[52:53]
	v_pk_mul_f32 v[8:9], v[8:9], v[36:37]
	s_nop 1
	v_cvt_pk_bf16_f32 v6, v6, v7
	s_nop 0
	s_nop 1
	v_cvt_pk_bf16_f32 v7, v8, v9
	global_store_dwordx2 v26, v[6:7], s[8:9]
	s_waitcnt vmcnt(6)
	v_mov_b64_e32 v[28:29], v[100:101]
	v_mov_b64_e32 v[30:31], v[102:103]
	v_mov_b64_e32 v[34:35], v[106:107]
	v_mov_b64_e32 v[36:37], v[108:109]
	v_mov_b64_e32 v[42:43], v[114:115]
	v_mov_b32_e32 v26, v118
	v_mov_b64_e32 v[6:7], v[60:61]
	v_mov_b64_e32 v[8:9], v[62:63]
	v_mov_b64_e32 v[10:11], v[64:65]
	v_mov_b64_e32 v[12:13], v[66:67]
	s_min_i32 s0, s20, 0xffff
	s_ashr_i32 s0, s0, 3
	s_lshl_b32 s1, s0, 11
	v_add_u32_e32 v121, s1, v124
	v_lshlrev_b32_e32 v118, 1, v121
	v_add_u32_e32 v121, 0x2000000, v121
	global_load_dwordx2 v[100:101], v118, s[38:39]
	global_load_dwordx2 v[102:103], v118, s[18:19]
	global_load_dwordx2 v[106:107], v118, s[68:69]
	global_load_dwordx2 v[108:109], v118, s[56:57]
	global_load_dword v114, v121, s[38:39]
	global_load_dword v115, v121, s[18:19]
	s_add_i32 s20, s20, s22
	v_lshlrev_b32_e32 v44, 16, v28
	v_and_b32_e32 v45, 0xffff0000, v28
	v_lshlrev_b32_e32 v28, 16, v29
	v_and_b32_e32 v29, 0xffff0000, v29
	v_lshlrev_b32_e32 v46, 16, v30
	v_and_b32_e32 v47, 0xffff0000, v30
	v_lshlrev_b32_e32 v30, 16, v31
	v_and_b32_e32 v31, 0xffff0000, v31
	v_pk_add_f32 v[28:29], v[28:29], v[30:31]
	v_pk_add_f32 v[30:31], v[44:45], v[46:47]
	v_add_f32_e32 v0, v30, v31
	v_add_f32_e32 v0, v28, v0
	v_add_f32_e32 v0, v29, v0
	s_nop 1
	v_add_f32_dpp v0, v0, v0 quad_perm:[1,0,3,2] row_mask:0xf bank_mask:0xf bound_ctrl:1
	s_nop 0
	v_add_f32_dpp v0, v0, v0 quad_perm:[2,3,0,1] row_mask:0xf bank_mask:0xf bound_ctrl:1
	s_nop 1
	v_add_f32_dpp v0, v0, v0 row_half_mirror row_mask:0xf bank_mask:0xf bound_ctrl:1
	s_nop 1
	v_add_f32_dpp v0, v0, v0 row_ror:8 row_mask:0xf bank_mask:0xf bound_ctrl:1
	v_fmamk_f32 v31, v0, 0xbc800000, v31
	v_fmac_f32_e32 v30, 0xbc800000, v0
	v_fmamk_f32 v29, v0, 0xbc800000, v29
	v_fmac_f32_e32 v28, 0xbc800000, v0
	v_pk_mul_f32 v[18:19], v[30:31], v[30:31]
	v_pk_mul_f32 v[14:15], v[28:29], v[28:29]
	v_add_f32_e32 v5, v18, v19
	v_add_f32_e32 v5, v14, v5
	v_add_f32_e32 v5, v15, v5
	v_add_f32_e32 v0, v42, v43
	v_lshlrev_b32_e32 v50, 16, v34
	v_add_f32_dpp v5, v5, v5 quad_perm:[1,0,3,2] row_mask:0xf bank_mask:0xf bound_ctrl:1
	v_add_f32_dpp v0, v0, v0 quad_perm:[1,0,3,2] row_mask:0xf bank_mask:0xf bound_ctrl:1
	v_and_b32_e32 v51, 0xffff0000, v34
	v_add_f32_dpp v5, v5, v5 quad_perm:[2,3,0,1] row_mask:0xf bank_mask:0xf bound_ctrl:1
	v_add_f32_dpp v0, v0, v0 quad_perm:[2,3,0,1] row_mask:0xf bank_mask:0xf bound_ctrl:1
	v_lshlrev_b32_e32 v34, 16, v35
	v_add_f32_dpp v5, v5, v5 row_half_mirror row_mask:0xf bank_mask:0xf bound_ctrl:1
	v_add_f32_dpp v0, v0, v0 row_half_mirror row_mask:0xf bank_mask:0xf bound_ctrl:1
	v_and_b32_e32 v35, 0xffff0000, v35
	v_add_f32_dpp v5, v5, v5 row_ror:8 row_mask:0xf bank_mask:0xf bound_ctrl:1
	v_fmamk_f32 v5, v5, 0x3c800000, v3
	v_mul_f32_e32 v14, 0x4f800000, v5
	v_cmp_gt_f32_e32 vcc, s24, v5
	v_add_f32_dpp v0, v0, v0 row_ror:8 row_mask:0xf bank_mask:0xf bound_ctrl:1
	v_lshlrev_b32_e32 v52, 16, v36
	v_cndmask_b32_e32 v5, v5, v14, vcc
	v_sqrt_f32_e32 v14, v5
	v_and_b32_e32 v53, 0xffff0000, v36
	v_lshlrev_b32_e32 v36, 16, v37
	v_and_b32_e32 v37, 0xffff0000, v37
	v_add_u32_e32 v15, -1, v14
	v_add_u32_e32 v16, 1, v14
	v_fma_f32 v17, -v15, v14, v5
	v_fma_f32 v18, -v16, v14, v5
	v_cmp_ge_f32_e64 s[6:7], 0, v17
	s_nop 1
	v_cndmask_b32_e64 v14, v14, v15, s[6:7]
	v_cmp_lt_f32_e64 s[6:7], 0, v18
	s_nop 1
	v_cndmask_b32_e64 v14, v14, v16, s[6:7]
	v_mul_f32_e32 v15, 0x37800000, v14
	v_cndmask_b32_e32 v14, v14, v15, vcc
	v_cmp_class_f32_e32 vcc, v5, v4
	s_nop 1
	v_cndmask_b32_e32 v5, v14, v5, vcc
	v_div_scale_f32 v14, s[0:1], v5, v5, 1.0
	v_rcp_f32_e32 v16, v14
	v_div_scale_f32 v15, vcc, 1.0, v5, 1.0
	v_fma_f32 v17, -v14, v16, 1.0
	v_fmac_f32_e32 v16, v17, v16
	v_mul_f32_e32 v17, v15, v16
	v_fma_f32 v18, -v14, v17, v15
	v_fmac_f32_e32 v17, v18, v16
	v_fma_f32 v14, -v14, v17, v15
	v_div_fmas_f32 v14, v14, v16, v17
	v_div_fixup_f32 v14, v14, v5, 1.0
	v_pk_mul_f32 v[16:17], v[30:31], v[14:15] op_sel_hi:[1,0]
	v_pk_mul_f32 v[14:15], v[28:29], v[14:15] op_sel_hi:[1,0]
	v_pk_fma_f32 v[6:7], v[6:7], v[16:17], v[10:11]
	v_pk_fma_f32 v[8:9], v[8:9], v[14:15], v[12:13]
	v_pk_fma_f32 v[6:7], v[0:1], v[50:51], v[6:7] op_sel_hi:[0,1,1]
	v_pk_fma_f32 v[8:9], v[0:1], v[34:35], v[8:9] op_sel_hi:[0,1,1]
	v_pk_mul_f32 v[6:7], v[6:7], v[52:53]
	v_pk_mul_f32 v[8:9], v[8:9], v[36:37]
	s_nop 1
	v_cvt_pk_bf16_f32 v6, v6, v7
	s_nop 0
	s_nop 1
	v_cvt_pk_bf16_f32 v7, v8, v9
	global_store_dwordx2 v26, v[6:7], s[8:9]
	s_sub_u32 s4, s4, 1
	s_cmp_lg_u32 s4, 0
	s_cbranch_scc1 .Lp6_loop
